# EpiFinal: nt (streaming) hint on the 32 f32 output stores per lane (v59 + finalnt)
# baseline (speedup 1.0000x reference)
.LBB0_2145:
	s_waitcnt vmcnt(0) lgkmcnt(0)
	s_barrier
	v_lshlrev_b64 v[140:141], 2, v[128:129]
	v_lshl_add_u64 v[128:129], s[12:13], 0, v[140:141]
	global_load_dwordx4 v[180:183], v[128:129], off
	global_load_dwordx4 v[184:187], v[128:129], off offset:16
	global_load_dwordx4 v[188:191], v[128:129], off offset:512
	global_load_dwordx4 v[196:199], v[128:129], off offset:528
	global_load_dword v172, v[112:113], off sc1
	global_load_dword v173, v[112:113], off offset:64 sc1
	global_load_dword v174, v[112:113], off offset:128 sc1
	global_load_dword v175, v[112:113], off offset:192 sc1
	global_load_dword v176, v[112:113], off offset:512 sc1
	global_load_dword v177, v[112:113], off offset:576 sc1
	global_load_dword v178, v[112:113], off offset:640 sc1
	global_load_dword v179, v[112:113], off offset:704 sc1
	s_nop 0
	s_nop 0
	v_mov_b32_e32 v153, 0x358637bd
	s_mov_b32 s4, 0xf800000
	s_waitcnt vmcnt(7)
	v_mov_b32_e32 v152, v172
	v_fmamk_f32 v152, v152, 0x3a000000, v153
	v_mul_f32_e32 v156, 0x4f800000, v152
	v_cmp_gt_f32_e32 vcc, s4, v152
	s_nop 1
	v_cndmask_b32_e32 v168, v152, v156, vcc
	v_sqrt_f32_e32 v169, v168
	v_lshl_add_u64 v[156:157], v[158:159], 2, s[8:9]
	v_mov_b32_e32 v152, 0x260
	v_add_u32_e32 v158, -1, v169
	v_add_u32_e32 v159, 1, v169
	v_fma_f32 v170, -v158, v169, v168
	v_fma_f32 v171, -v159, v169, v168
	v_cmp_ge_f32_e64 s[0:1], 0, v170
	s_nop 1
	v_cndmask_b32_e64 v158, v169, v158, s[0:1]
	v_cmp_lt_f32_e64 s[0:1], 0, v171
	s_nop 1
	v_cndmask_b32_e64 v158, v158, v159, s[0:1]
	v_mul_f32_e32 v159, 0x37800000, v158
	v_cndmask_b32_e32 v158, v158, v159, vcc
	v_cmp_class_f32_e32 vcc, v168, v152
	s_nop 1
	v_cndmask_b32_e32 v158, v158, v168, vcc
	v_div_scale_f32 v159, s[0:1], v158, v158, 1.0
	v_rcp_f32_e32 v170, v159
	v_lshl_add_u64 v[168:169], v[156:157], 0, v[140:141]
	v_div_scale_f32 v156, vcc, 1.0, v158, 1.0
	v_fma_f32 v157, -v159, v170, 1.0
	v_fmac_f32_e32 v170, v157, v170
	v_mul_f32_e32 v157, v156, v170
	v_fma_f32 v171, -v159, v157, v156
	v_fmac_f32_e32 v157, v171, v170
	v_fma_f32 v156, -v159, v157, v156
	v_div_fmas_f32 v156, v156, v170, v157
	v_div_fixup_f32 v170, v156, v158, 1.0
	v_pk_mul_f32 v[132:133], v[132:133], v[170:171] op_sel_hi:[1,0]
	v_pk_mul_f32 v[126:127], v[126:127], v[170:171] op_sel_hi:[1,0]
	v_pk_mul_f32 v[156:157], v[124:125], v[170:171] op_sel_hi:[1,0]
	v_pk_mul_f32 v[158:159], v[122:123], v[170:171] op_sel_hi:[1,0]
	v_mov_b32_e32 v160, v180
	v_mov_b32_e32 v161, v181
	v_mov_b32_e32 v162, v182
	v_mov_b32_e32 v163, v183
	v_pk_mul_f32 v[124:125], v[162:163], v[126:127]
	v_pk_mul_f32 v[122:123], v[160:161], v[132:133]
	v_mov_b32_e32 v164, v184
	v_mov_b32_e32 v165, v185
	v_mov_b32_e32 v166, v186
	v_mov_b32_e32 v167, v187
	v_pk_mul_f32 v[158:159], v[166:167], v[158:159]
	v_pk_mul_f32 v[156:157], v[164:165], v[156:157]
	global_store_dwordx4 v[168:169], v[122:125], off nt
	global_store_dwordx4 v[168:169], v[156:159], off offset:16 nt
	s_nop 0
	s_nop 0
	s_nop 0
	v_pk_mul_f32 v[118:119], v[118:119], v[170:171] op_sel_hi:[1,0]
	v_pk_mul_f32 v[116:117], v[116:117], v[170:171] op_sel_hi:[1,0]
	v_pk_mul_f32 v[132:133], v[114:115], v[170:171] op_sel_hi:[1,0]
	v_pk_mul_f32 v[120:121], v[120:121], v[170:171] op_sel_hi:[1,0]
	v_lshl_add_u64 v[126:127], v[136:137], 2, s[2:3]
	v_mov_b32_e32 v122, v188
	v_mov_b32_e32 v123, v189
	v_mov_b32_e32 v124, v190
	v_mov_b32_e32 v125, v191
	v_pk_mul_f32 v[114:115], v[122:123], v[116:117]
	v_pk_mul_f32 v[116:117], v[124:125], v[118:119]
	v_mov_b32_e32 v156, v196
	v_mov_b32_e32 v157, v197
	v_mov_b32_e32 v158, v198
	v_mov_b32_e32 v159, v199
	v_pk_mul_f32 v[118:119], v[156:157], v[120:121]
	v_pk_mul_f32 v[120:121], v[158:159], v[132:133]
	global_store_dwordx4 v[168:169], v[114:117], off offset:512 nt
	global_store_dwordx4 v[168:169], v[118:121], off offset:528 nt
	s_nop 0
	s_nop 0
	s_nop 0
	s_nop 0
	s_waitcnt vmcnt(6)
	v_mov_b32_e32 v122, v173
	v_fmamk_f32 v122, v122, 0x3a000000, v153
	v_mul_f32_e32 v123, 0x4f800000, v122
	v_cmp_gt_f32_e32 vcc, s4, v122
	s_nop 1
	v_cndmask_b32_e32 v124, v122, v123, vcc
	v_sqrt_f32_e32 v125, v124
	v_lshl_add_u64 v[122:123], v[154:155], 2, s[8:9]
	v_lshl_add_u64 v[122:123], v[122:123], 0, v[140:141]
	v_add_u32_e32 v126, -1, v125
	v_add_u32_e32 v127, 1, v125
	v_fma_f32 v132, -v126, v125, v124
	v_fma_f32 v133, -v127, v125, v124
	v_cmp_ge_f32_e64 s[0:1], 0, v132
	s_nop 1
	v_cndmask_b32_e64 v125, v125, v126, s[0:1]
	v_cmp_lt_f32_e64 s[0:1], 0, v133
	s_nop 1
	v_cndmask_b32_e64 v125, v125, v127, s[0:1]
	v_mul_f32_e32 v126, 0x37800000, v125
	v_cndmask_b32_e32 v125, v125, v126, vcc
	v_cmp_class_f32_e32 vcc, v124, v152
	s_nop 1
	v_cndmask_b32_e32 v124, v125, v124, vcc
	v_div_scale_f32 v125, s[0:1], v124, v124, 1.0
	v_rcp_f32_e32 v126, v125
	v_div_scale_f32 v127, vcc, 1.0, v124, 1.0
	v_fma_f32 v132, -v125, v126, 1.0
	v_fmac_f32_e32 v126, v132, v126
	v_mul_f32_e32 v132, v127, v126
	v_fma_f32 v133, -v125, v132, v127
	v_fmac_f32_e32 v132, v133, v126
	v_fma_f32 v125, -v125, v132, v127
	v_div_fmas_f32 v125, v125, v126, v132
	v_div_fixup_f32 v124, v125, v124, 1.0
	v_pk_mul_f32 v[126:127], v[130:131], v[124:125] op_sel_hi:[1,0]
	v_pk_mul_f32 v[110:111], v[110:111], v[124:125] op_sel_hi:[1,0]
	v_pk_mul_f32 v[130:131], v[104:105], v[124:125] op_sel_hi:[1,0]
	v_pk_mul_f32 v[132:133], v[106:107], v[124:125] op_sel_hi:[1,0]
	v_mov_b32_e32 v114, v180
	v_mov_b32_e32 v115, v181
	v_mov_b32_e32 v116, v182
	v_mov_b32_e32 v117, v183
	v_pk_mul_f32 v[106:107], v[116:117], v[110:111]
	v_pk_mul_f32 v[104:105], v[114:115], v[126:127]
	v_mov_b32_e32 v118, v184
	v_mov_b32_e32 v119, v185
	v_mov_b32_e32 v120, v186
	v_mov_b32_e32 v121, v187
	v_pk_mul_f32 v[116:117], v[120:121], v[132:133]
	v_pk_mul_f32 v[114:115], v[118:119], v[130:131]
	global_store_dwordx4 v[122:123], v[104:107], off nt
	global_store_dwordx4 v[122:123], v[114:117], off offset:16 nt
	s_nop 0
	s_nop 0
	s_nop 0
	v_pk_mul_f32 v[102:103], v[102:103], v[124:125] op_sel_hi:[1,0]
	v_pk_mul_f32 v[100:101], v[100:101], v[124:125] op_sel_hi:[1,0]
	v_pk_mul_f32 v[118:119], v[98:99], v[124:125] op_sel_hi:[1,0]
	v_pk_mul_f32 v[120:121], v[96:97], v[124:125] op_sel_hi:[1,0]
	v_lshl_add_u64 v[110:111], v[134:135], 2, s[2:3]
	v_mov_b32_e32 v104, v188
	v_mov_b32_e32 v105, v189
	v_mov_b32_e32 v106, v190
	v_mov_b32_e32 v107, v191
	v_pk_mul_f32 v[96:97], v[104:105], v[100:101]
	v_pk_mul_f32 v[98:99], v[106:107], v[102:103]
	v_mov_b32_e32 v114, v196
	v_mov_b32_e32 v115, v197
	v_mov_b32_e32 v116, v198
	v_mov_b32_e32 v117, v199
	v_pk_mul_f32 v[100:101], v[114:115], v[120:121]
	v_pk_mul_f32 v[102:103], v[116:117], v[118:119]
	global_store_dwordx4 v[122:123], v[96:99], off offset:512 nt
	global_store_dwordx4 v[122:123], v[100:103], off offset:528 nt
	s_nop 0
	s_nop 0
	s_nop 0
	s_nop 0
	s_waitcnt vmcnt(5)
	v_mov_b32_e32 v104, v174
	v_fmamk_f32 v104, v104, 0x3a000000, v153
	v_mul_f32_e32 v105, 0x4f800000, v104
	v_cmp_gt_f32_e32 vcc, s4, v104
	s_nop 1
	v_cndmask_b32_e32 v106, v104, v105, vcc
	v_sqrt_f32_e32 v107, v106
	v_lshl_add_u64 v[104:105], v[150:151], 2, s[8:9]
	v_lshl_add_u64 v[104:105], v[104:105], 0, v[140:141]
	v_add_u32_e32 v110, -1, v107
	v_add_u32_e32 v111, 1, v107
	v_fma_f32 v114, -v110, v107, v106
	v_fma_f32 v115, -v111, v107, v106
	v_cmp_ge_f32_e64 s[0:1], 0, v114
	s_nop 1
	v_cndmask_b32_e64 v107, v107, v110, s[0:1]
	v_cmp_lt_f32_e64 s[0:1], 0, v115
	s_nop 1
	v_cndmask_b32_e64 v107, v107, v111, s[0:1]
	v_mul_f32_e32 v110, 0x37800000, v107
	v_cndmask_b32_e32 v107, v107, v110, vcc
	v_cmp_class_f32_e32 vcc, v106, v152
	s_nop 1
	v_cndmask_b32_e32 v106, v107, v106, vcc
	v_div_scale_f32 v107, s[0:1], v106, v106, 1.0
	v_rcp_f32_e32 v110, v107
	v_div_scale_f32 v111, vcc, 1.0, v106, 1.0
	v_fma_f32 v114, -v107, v110, 1.0
	v_fmac_f32_e32 v110, v114, v110
	v_mul_f32_e32 v114, v111, v110
	v_fma_f32 v115, -v107, v114, v111
	v_fmac_f32_e32 v114, v115, v110
	v_fma_f32 v107, -v107, v114, v111
	v_div_fmas_f32 v107, v107, v110, v114
	v_div_fixup_f32 v106, v107, v106, 1.0
	v_pk_mul_f32 v[92:93], v[92:93], v[106:107] op_sel_hi:[1,0]
	v_pk_mul_f32 v[94:95], v[94:95], v[106:107] op_sel_hi:[1,0]
	v_pk_mul_f32 v[110:111], v[88:89], v[106:107] op_sel_hi:[1,0]
	v_pk_mul_f32 v[114:115], v[90:91], v[106:107] op_sel_hi:[1,0]
	v_mov_b32_e32 v96, v180
	v_mov_b32_e32 v97, v181
	v_mov_b32_e32 v98, v182
	v_mov_b32_e32 v99, v183
	v_pk_mul_f32 v[90:91], v[98:99], v[94:95]
	v_pk_mul_f32 v[88:89], v[96:97], v[92:93]
	v_mov_b32_e32 v100, v184
	v_mov_b32_e32 v101, v185
	v_mov_b32_e32 v102, v186
	v_mov_b32_e32 v103, v187
	v_pk_mul_f32 v[94:95], v[102:103], v[114:115]
	v_pk_mul_f32 v[92:93], v[100:101], v[110:111]
	global_store_dwordx4 v[104:105], v[88:91], off nt
	global_store_dwordx4 v[104:105], v[92:95], off offset:16 nt
	s_nop 0
	s_nop 0
	s_nop 0
	v_pk_mul_f32 v[86:87], v[86:87], v[106:107] op_sel_hi:[1,0]
	v_pk_mul_f32 v[84:85], v[84:85], v[106:107] op_sel_hi:[1,0]
	v_pk_mul_f32 v[98:99], v[82:83], v[106:107] op_sel_hi:[1,0]
	v_pk_mul_f32 v[100:101], v[80:81], v[106:107] op_sel_hi:[1,0]
	v_lshl_add_u64 v[96:97], v[108:109], 2, s[2:3]
	v_mov_b32_e32 v88, v188
	v_mov_b32_e32 v89, v189
	v_mov_b32_e32 v90, v190
	v_mov_b32_e32 v91, v191
	v_pk_mul_f32 v[80:81], v[88:89], v[84:85]
	v_pk_mul_f32 v[82:83], v[90:91], v[86:87]
	v_mov_b32_e32 v92, v196
	v_mov_b32_e32 v93, v197
	v_mov_b32_e32 v94, v198
	v_mov_b32_e32 v95, v199
	v_pk_mul_f32 v[84:85], v[92:93], v[100:101]
	v_pk_mul_f32 v[86:87], v[94:95], v[98:99]
	global_store_dwordx4 v[104:105], v[80:83], off offset:512 nt
	global_store_dwordx4 v[104:105], v[84:87], off offset:528 nt
	s_nop 0
	s_nop 0
	s_nop 0
	s_nop 0
	s_waitcnt vmcnt(4)
	v_mov_b32_e32 v88, v175
	v_fmamk_f32 v88, v88, 0x3a000000, v153
	v_mul_f32_e32 v89, 0x4f800000, v88
	v_cmp_gt_f32_e32 vcc, s4, v88
	s_nop 1
	v_cndmask_b32_e32 v90, v88, v89, vcc
	v_sqrt_f32_e32 v91, v90
	v_lshl_add_u64 v[88:89], v[148:149], 2, s[8:9]
	v_lshl_add_u64 v[88:89], v[88:89], 0, v[140:141]
	v_add_u32_e32 v92, -1, v91
	v_add_u32_e32 v93, 1, v91
	v_fma_f32 v94, -v92, v91, v90
	v_fma_f32 v95, -v93, v91, v90
	v_cmp_ge_f32_e64 s[0:1], 0, v94
	s_nop 1
	v_cndmask_b32_e64 v91, v91, v92, s[0:1]
	v_cmp_lt_f32_e64 s[0:1], 0, v95
	s_nop 1
	v_cndmask_b32_e64 v91, v91, v93, s[0:1]
	v_mul_f32_e32 v92, 0x37800000, v91
	v_cndmask_b32_e32 v91, v91, v92, vcc
	v_cmp_class_f32_e32 vcc, v90, v152
	s_nop 1
	v_cndmask_b32_e32 v90, v91, v90, vcc
	v_div_scale_f32 v91, s[0:1], v90, v90, 1.0
	v_rcp_f32_e32 v92, v91
	v_div_scale_f32 v93, vcc, 1.0, v90, 1.0
	v_fma_f32 v94, -v91, v92, 1.0
	v_fmac_f32_e32 v92, v94, v92
	v_mul_f32_e32 v94, v93, v92
	v_fma_f32 v95, -v91, v94, v93
	v_fmac_f32_e32 v94, v95, v92
	v_fma_f32 v91, -v91, v94, v93
	v_div_fmas_f32 v91, v91, v92, v94
	v_div_fixup_f32 v90, v91, v90, 1.0
	v_pk_mul_f32 v[76:77], v[76:77], v[90:91] op_sel_hi:[1,0]
	v_pk_mul_f32 v[78:79], v[78:79], v[90:91] op_sel_hi:[1,0]
	v_pk_mul_f32 v[92:93], v[72:73], v[90:91] op_sel_hi:[1,0]
	v_pk_mul_f32 v[94:95], v[74:75], v[90:91] op_sel_hi:[1,0]
	v_mov_b32_e32 v80, v180
	v_mov_b32_e32 v81, v181
	v_mov_b32_e32 v82, v182
	v_mov_b32_e32 v83, v183
	v_pk_mul_f32 v[74:75], v[82:83], v[78:79]
	v_pk_mul_f32 v[72:73], v[80:81], v[76:77]
	v_mov_b32_e32 v84, v184
	v_mov_b32_e32 v85, v185
	v_mov_b32_e32 v86, v186
	v_mov_b32_e32 v87, v187
	v_pk_mul_f32 v[78:79], v[86:87], v[94:95]
	v_pk_mul_f32 v[76:77], v[84:85], v[92:93]
	global_store_dwordx4 v[88:89], v[72:75], off nt
	global_store_dwordx4 v[88:89], v[76:79], off offset:16 nt
	s_nop 0
	s_nop 0
	s_nop 0
	v_pk_mul_f32 v[70:71], v[70:71], v[90:91] op_sel_hi:[1,0]
	v_pk_mul_f32 v[68:69], v[68:69], v[90:91] op_sel_hi:[1,0]
	v_pk_mul_f32 v[80:81], v[66:67], v[90:91] op_sel_hi:[1,0]
	v_pk_mul_f32 v[82:83], v[64:65], v[90:91] op_sel_hi:[1,0]
	v_mov_b32_e32 v72, v188
	v_mov_b32_e32 v73, v189
	v_mov_b32_e32 v74, v190
	v_mov_b32_e32 v75, v191
	v_pk_mul_f32 v[64:65], v[72:73], v[68:69]
	v_pk_mul_f32 v[66:67], v[74:75], v[70:71]
	v_mov_b32_e32 v76, v196
	v_mov_b32_e32 v77, v197
	v_mov_b32_e32 v78, v198
	v_mov_b32_e32 v79, v199
	v_pk_mul_f32 v[68:69], v[76:77], v[82:83]
	v_pk_mul_f32 v[70:71], v[78:79], v[80:81]
	global_store_dwordx4 v[88:89], v[64:67], off offset:512 nt
	global_store_dwordx4 v[88:89], v[68:71], off offset:528 nt
	s_nop 0
	s_nop 0
	s_nop 0
	s_nop 0
	s_waitcnt vmcnt(3)
	v_mov_b32_e32 v72, v176
	v_fmamk_f32 v72, v72, 0x3a000000, v153
	v_mul_f32_e32 v73, 0x4f800000, v72
	v_cmp_gt_f32_e32 vcc, s4, v72
	s_nop 1
	v_cndmask_b32_e32 v74, v72, v73, vcc
	v_sqrt_f32_e32 v75, v74
	v_lshl_add_u64 v[72:73], v[146:147], 2, s[8:9]
	v_lshl_add_u64 v[72:73], v[72:73], 0, v[140:141]
	v_add_u32_e32 v76, -1, v75
	v_add_u32_e32 v77, 1, v75
	v_fma_f32 v78, -v76, v75, v74
	v_fma_f32 v79, -v77, v75, v74
	v_cmp_ge_f32_e64 s[0:1], 0, v78
	s_nop 1
	v_cndmask_b32_e64 v75, v75, v76, s[0:1]
	v_cmp_lt_f32_e64 s[0:1], 0, v79
	s_nop 1
	v_cndmask_b32_e64 v75, v75, v77, s[0:1]
	v_mul_f32_e32 v76, 0x37800000, v75
	v_cndmask_b32_e32 v75, v75, v76, vcc
	v_cmp_class_f32_e32 vcc, v74, v152
	s_nop 1
	v_cndmask_b32_e32 v74, v75, v74, vcc
	v_div_scale_f32 v75, s[0:1], v74, v74, 1.0
	v_rcp_f32_e32 v76, v75
	v_div_scale_f32 v77, vcc, 1.0, v74, 1.0
	v_fma_f32 v78, -v75, v76, 1.0
	v_fmac_f32_e32 v76, v78, v76
	v_mul_f32_e32 v78, v77, v76
	v_fma_f32 v79, -v75, v78, v77
	v_fmac_f32_e32 v78, v79, v76
	v_fma_f32 v75, -v75, v78, v77
	v_div_fmas_f32 v75, v75, v76, v78
	v_div_fixup_f32 v74, v75, v74, 1.0
	v_pk_mul_f32 v[60:61], v[60:61], v[74:75] op_sel_hi:[1,0]
	v_pk_mul_f32 v[62:63], v[62:63], v[74:75] op_sel_hi:[1,0]
	v_pk_mul_f32 v[76:77], v[56:57], v[74:75] op_sel_hi:[1,0]
	v_pk_mul_f32 v[78:79], v[58:59], v[74:75] op_sel_hi:[1,0]
	v_mov_b32_e32 v64, v180
	v_mov_b32_e32 v65, v181
	v_mov_b32_e32 v66, v182
	v_mov_b32_e32 v67, v183
	v_pk_mul_f32 v[58:59], v[66:67], v[62:63]
	v_pk_mul_f32 v[56:57], v[64:65], v[60:61]
	v_mov_b32_e32 v68, v184
	v_mov_b32_e32 v69, v185
	v_mov_b32_e32 v70, v186
	v_mov_b32_e32 v71, v187
	v_pk_mul_f32 v[62:63], v[70:71], v[78:79]
	v_pk_mul_f32 v[60:61], v[68:69], v[76:77]
	global_store_dwordx4 v[72:73], v[56:59], off nt
	global_store_dwordx4 v[72:73], v[60:63], off offset:16 nt
	s_nop 0
	s_nop 0
	s_nop 0
	v_pk_mul_f32 v[54:55], v[54:55], v[74:75] op_sel_hi:[1,0]
	v_pk_mul_f32 v[52:53], v[52:53], v[74:75] op_sel_hi:[1,0]
	v_pk_mul_f32 v[64:65], v[50:51], v[74:75] op_sel_hi:[1,0]
	v_pk_mul_f32 v[66:67], v[48:49], v[74:75] op_sel_hi:[1,0]
	v_mov_b32_e32 v56, v188
	v_mov_b32_e32 v57, v189
	v_mov_b32_e32 v58, v190
	v_mov_b32_e32 v59, v191
	v_pk_mul_f32 v[48:49], v[56:57], v[52:53]
	v_pk_mul_f32 v[50:51], v[58:59], v[54:55]
	v_mov_b32_e32 v60, v196
	v_mov_b32_e32 v61, v197
	v_mov_b32_e32 v62, v198
	v_mov_b32_e32 v63, v199
	v_pk_mul_f32 v[52:53], v[60:61], v[66:67]
	v_pk_mul_f32 v[54:55], v[62:63], v[64:65]
	global_store_dwordx4 v[72:73], v[48:51], off offset:512 nt
	global_store_dwordx4 v[72:73], v[52:55], off offset:528 nt
	s_nop 0
	s_nop 0
	s_nop 0
	s_nop 0
	s_waitcnt vmcnt(2)
	v_mov_b32_e32 v56, v177
	v_fmamk_f32 v56, v56, 0x3a000000, v153
	v_mul_f32_e32 v57, 0x4f800000, v56
	v_cmp_gt_f32_e32 vcc, s4, v56
	s_nop 1
	v_cndmask_b32_e32 v58, v56, v57, vcc
	v_sqrt_f32_e32 v59, v58
	v_lshl_add_u64 v[56:57], v[144:145], 2, s[8:9]
	v_lshl_add_u64 v[56:57], v[56:57], 0, v[140:141]
	v_add_u32_e32 v60, -1, v59
	v_add_u32_e32 v61, 1, v59
	v_fma_f32 v62, -v60, v59, v58
	v_fma_f32 v63, -v61, v59, v58
	v_cmp_ge_f32_e64 s[0:1], 0, v62
	s_nop 1
	v_cndmask_b32_e64 v59, v59, v60, s[0:1]
	v_cmp_lt_f32_e64 s[0:1], 0, v63
	s_nop 1
	v_cndmask_b32_e64 v59, v59, v61, s[0:1]
	v_mul_f32_e32 v60, 0x37800000, v59
	v_cndmask_b32_e32 v59, v59, v60, vcc
	v_cmp_class_f32_e32 vcc, v58, v152
	s_nop 1
	v_cndmask_b32_e32 v58, v59, v58, vcc
	v_div_scale_f32 v59, s[0:1], v58, v58, 1.0
	v_rcp_f32_e32 v60, v59
	v_div_scale_f32 v61, vcc, 1.0, v58, 1.0
	v_fma_f32 v62, -v59, v60, 1.0
	v_fmac_f32_e32 v60, v62, v60
	v_mul_f32_e32 v62, v61, v60
	v_fma_f32 v63, -v59, v62, v61
	v_fmac_f32_e32 v62, v63, v60
	v_fma_f32 v59, -v59, v62, v61
	v_div_fmas_f32 v59, v59, v60, v62
	v_div_fixup_f32 v58, v59, v58, 1.0
	v_pk_mul_f32 v[44:45], v[44:45], v[58:59] op_sel_hi:[1,0]
	v_pk_mul_f32 v[46:47], v[46:47], v[58:59] op_sel_hi:[1,0]
	v_pk_mul_f32 v[60:61], v[40:41], v[58:59] op_sel_hi:[1,0]
	v_pk_mul_f32 v[62:63], v[42:43], v[58:59] op_sel_hi:[1,0]
	v_mov_b32_e32 v48, v180
	v_mov_b32_e32 v49, v181
	v_mov_b32_e32 v50, v182
	v_mov_b32_e32 v51, v183
	v_pk_mul_f32 v[42:43], v[50:51], v[46:47]
	v_pk_mul_f32 v[40:41], v[48:49], v[44:45]
	v_mov_b32_e32 v52, v184
	v_mov_b32_e32 v53, v185
	v_mov_b32_e32 v54, v186
	v_mov_b32_e32 v55, v187
	v_pk_mul_f32 v[46:47], v[54:55], v[62:63]
	v_pk_mul_f32 v[44:45], v[52:53], v[60:61]
	global_store_dwordx4 v[56:57], v[40:43], off nt
	global_store_dwordx4 v[56:57], v[44:47], off offset:16 nt
	s_nop 0
	s_nop 0
	s_nop 0
	v_pk_mul_f32 v[38:39], v[38:39], v[58:59] op_sel_hi:[1,0]
	v_pk_mul_f32 v[36:37], v[36:37], v[58:59] op_sel_hi:[1,0]
	v_pk_mul_f32 v[48:49], v[34:35], v[58:59] op_sel_hi:[1,0]
	v_pk_mul_f32 v[50:51], v[32:33], v[58:59] op_sel_hi:[1,0]
	v_mov_b32_e32 v40, v188
	v_mov_b32_e32 v41, v189
	v_mov_b32_e32 v42, v190
	v_mov_b32_e32 v43, v191
	v_pk_mul_f32 v[32:33], v[40:41], v[36:37]
	v_pk_mul_f32 v[34:35], v[42:43], v[38:39]
	v_mov_b32_e32 v44, v196
	v_mov_b32_e32 v45, v197
	v_mov_b32_e32 v46, v198
	v_mov_b32_e32 v47, v199
	v_pk_mul_f32 v[36:37], v[44:45], v[50:51]
	v_pk_mul_f32 v[38:39], v[46:47], v[48:49]
	global_store_dwordx4 v[56:57], v[32:35], off offset:512 nt
	global_store_dwordx4 v[56:57], v[36:39], off offset:528 nt
	s_nop 0
	s_nop 0
	s_nop 0
	s_nop 0
	s_waitcnt vmcnt(1)
	v_mov_b32_e32 v40, v178
	v_fmamk_f32 v40, v40, 0x3a000000, v153
	v_mul_f32_e32 v41, 0x4f800000, v40
	v_cmp_gt_f32_e32 vcc, s4, v40
	s_nop 1
	v_cndmask_b32_e32 v42, v40, v41, vcc
	v_sqrt_f32_e32 v43, v42
	v_lshl_add_u64 v[40:41], v[142:143], 2, s[8:9]
	v_lshl_add_u64 v[40:41], v[40:41], 0, v[140:141]
	v_add_u32_e32 v44, -1, v43
	v_add_u32_e32 v45, 1, v43
	v_fma_f32 v46, -v44, v43, v42
	v_fma_f32 v47, -v45, v43, v42
	v_cmp_ge_f32_e64 s[0:1], 0, v46
	s_nop 1
	v_cndmask_b32_e64 v43, v43, v44, s[0:1]
	v_cmp_lt_f32_e64 s[0:1], 0, v47
	s_nop 1
	v_cndmask_b32_e64 v43, v43, v45, s[0:1]
	v_mul_f32_e32 v44, 0x37800000, v43
	v_cndmask_b32_e32 v43, v43, v44, vcc
	v_cmp_class_f32_e32 vcc, v42, v152
	s_nop 1
	v_cndmask_b32_e32 v42, v43, v42, vcc
	v_div_scale_f32 v43, s[0:1], v42, v42, 1.0
	v_rcp_f32_e32 v44, v43
	v_div_scale_f32 v45, vcc, 1.0, v42, 1.0
	v_fma_f32 v46, -v43, v44, 1.0
	v_fmac_f32_e32 v44, v46, v44
	v_mul_f32_e32 v46, v45, v44
	v_fma_f32 v47, -v43, v46, v45
	v_fmac_f32_e32 v46, v47, v44
	v_fma_f32 v43, -v43, v46, v45
	v_div_fmas_f32 v43, v43, v44, v46
	v_div_fixup_f32 v42, v43, v42, 1.0
	v_pk_mul_f32 v[28:29], v[28:29], v[42:43] op_sel_hi:[1,0]
	v_pk_mul_f32 v[30:31], v[30:31], v[42:43] op_sel_hi:[1,0]
	v_pk_mul_f32 v[44:45], v[24:25], v[42:43] op_sel_hi:[1,0]
	v_pk_mul_f32 v[46:47], v[26:27], v[42:43] op_sel_hi:[1,0]
	v_mov_b32_e32 v32, v180
	v_mov_b32_e32 v33, v181
	v_mov_b32_e32 v34, v182
	v_mov_b32_e32 v35, v183
	v_pk_mul_f32 v[26:27], v[34:35], v[30:31]
	v_pk_mul_f32 v[24:25], v[32:33], v[28:29]
	v_mov_b32_e32 v36, v184
	v_mov_b32_e32 v37, v185
	v_mov_b32_e32 v38, v186
	v_mov_b32_e32 v39, v187
	v_pk_mul_f32 v[30:31], v[38:39], v[46:47]
	v_pk_mul_f32 v[28:29], v[36:37], v[44:45]
	global_store_dwordx4 v[40:41], v[24:27], off nt
	global_store_dwordx4 v[40:41], v[28:31], off offset:16 nt
	s_nop 0
	s_nop 0
	s_nop 0
	v_pk_mul_f32 v[22:23], v[22:23], v[42:43] op_sel_hi:[1,0]
	v_pk_mul_f32 v[20:21], v[20:21], v[42:43] op_sel_hi:[1,0]
	v_pk_mul_f32 v[32:33], v[18:19], v[42:43] op_sel_hi:[1,0]
	v_pk_mul_f32 v[34:35], v[16:17], v[42:43] op_sel_hi:[1,0]
	v_mov_b32_e32 v24, v188
	v_mov_b32_e32 v25, v189
	v_mov_b32_e32 v26, v190
	v_mov_b32_e32 v27, v191
	v_pk_mul_f32 v[16:17], v[24:25], v[20:21]
	v_pk_mul_f32 v[18:19], v[26:27], v[22:23]
	v_mov_b32_e32 v28, v196
	v_mov_b32_e32 v29, v197
	v_mov_b32_e32 v30, v198
	v_mov_b32_e32 v31, v199
	v_pk_mul_f32 v[20:21], v[28:29], v[34:35]
	v_pk_mul_f32 v[22:23], v[30:31], v[32:33]
	global_store_dwordx4 v[40:41], v[16:19], off offset:512 nt
	global_store_dwordx4 v[40:41], v[20:23], off offset:528 nt
	s_nop 0
	s_nop 0
	s_nop 0
	s_nop 0
	s_waitcnt vmcnt(0)
	v_mov_b32_e32 v24, v179
	v_fmac_f32_e32 v153, 0x3a000000, v24
	v_mul_f32_e32 v24, 0x4f800000, v153
	v_cmp_gt_f32_e32 vcc, s4, v153
	s_nop 1
	v_cndmask_b32_e32 v26, v153, v24, vcc
	v_sqrt_f32_e32 v27, v26
	v_lshl_add_u64 v[24:25], v[138:139], 2, s[8:9]
	v_lshl_add_u64 v[24:25], v[24:25], 0, v[140:141]
	v_add_u32_e32 v28, -1, v27
	v_add_u32_e32 v29, 1, v27
	v_fma_f32 v30, -v28, v27, v26
	v_fma_f32 v31, -v29, v27, v26
	v_cmp_ge_f32_e64 s[0:1], 0, v30
	s_nop 1
	v_cndmask_b32_e64 v27, v27, v28, s[0:1]
	v_cmp_lt_f32_e64 s[0:1], 0, v31
	s_nop 1
	v_cndmask_b32_e64 v27, v27, v29, s[0:1]
	v_mul_f32_e32 v28, 0x37800000, v27
	v_cndmask_b32_e32 v27, v27, v28, vcc
	v_cmp_class_f32_e32 vcc, v26, v152
	s_nop 1
	v_cndmask_b32_e32 v26, v27, v26, vcc
	v_div_scale_f32 v27, s[0:1], v26, v26, 1.0
	v_rcp_f32_e32 v28, v27
	v_div_scale_f32 v29, vcc, 1.0, v26, 1.0
	v_fma_f32 v30, -v27, v28, 1.0
	v_fmac_f32_e32 v28, v30, v28
	v_mul_f32_e32 v30, v29, v28
	v_fma_f32 v31, -v27, v30, v29
	v_fmac_f32_e32 v30, v31, v28
	v_fma_f32 v27, -v27, v30, v29
	v_div_fmas_f32 v27, v27, v28, v30
	v_div_fixup_f32 v26, v27, v26, 1.0
	v_pk_mul_f32 v[12:13], v[12:13], v[26:27] op_sel_hi:[1,0]
	v_pk_mul_f32 v[14:15], v[14:15], v[26:27] op_sel_hi:[1,0]
	v_pk_mul_f32 v[28:29], v[8:9], v[26:27] op_sel_hi:[1,0]
	v_pk_mul_f32 v[30:31], v[10:11], v[26:27] op_sel_hi:[1,0]
	v_mov_b32_e32 v16, v180
	v_mov_b32_e32 v17, v181
	v_mov_b32_e32 v18, v182
	v_mov_b32_e32 v19, v183
	v_pk_mul_f32 v[10:11], v[18:19], v[14:15]
	v_pk_mul_f32 v[8:9], v[16:17], v[12:13]
	v_mov_b32_e32 v20, v184
	v_mov_b32_e32 v21, v185
	v_mov_b32_e32 v22, v186
	v_mov_b32_e32 v23, v187
	v_pk_mul_f32 v[14:15], v[22:23], v[30:31]
	v_pk_mul_f32 v[12:13], v[20:21], v[28:29]
	global_store_dwordx4 v[24:25], v[8:11], off nt
	global_store_dwordx4 v[24:25], v[12:15], off offset:16 nt
	s_nop 0
	s_nop 0
	s_nop 0
	v_pk_mul_f32 v[6:7], v[6:7], v[26:27] op_sel_hi:[1,0]
	v_pk_mul_f32 v[4:5], v[4:5], v[26:27] op_sel_hi:[1,0]
	v_pk_mul_f32 v[16:17], v[2:3], v[26:27] op_sel_hi:[1,0]
	v_pk_mul_f32 v[18:19], v[0:1], v[26:27] op_sel_hi:[1,0]
	v_mov_b32_e32 v8, v188
	v_mov_b32_e32 v9, v189
	v_mov_b32_e32 v10, v190
	v_mov_b32_e32 v11, v191
	v_pk_mul_f32 v[0:1], v[8:9], v[4:5]
	v_pk_mul_f32 v[2:3], v[10:11], v[6:7]
	v_mov_b32_e32 v12, v196
	v_mov_b32_e32 v13, v197
	v_mov_b32_e32 v14, v198
	v_mov_b32_e32 v15, v199
	v_pk_mul_f32 v[4:5], v[12:13], v[18:19]
	v_pk_mul_f32 v[6:7], v[14:15], v[16:17]
	global_store_dwordx4 v[24:25], v[0:3], off offset:512 nt
	global_store_dwordx4 v[24:25], v[4:7], off offset:528 nt
	s_endpgm
